# v12 + staging-block tile descriptor (two tiles ahead) prefetched from LDS before the previous barrier: no ds_read->lgkmcnt(0) round trip in the staging path
# speedup vs baseline: 1.0048x; 1.0048x over previous
; DI void nsa_item(KA a, LAS unsigned char* lds, const int it) {
;     ...
;         of[0] = ot[0] * g0; of[1] = ot[1] * g0;
;         if (qb >= 16) {
.LBB0_794:
	v_add_f32_e32 v33, 1.0, v33
	v_rcp_f32_e32 v34, v33
	s_andn2_b64 vcc, exec, s[0:1]
	v_readlane_b32 s90, v254, 47
	v_pk_mul_f32 v[124:125], v[34:35], v[30:31] op_sel_hi:[0,1]
	v_pk_mul_f32 v[120:121], v[34:35], v[28:29] op_sel_hi:[0,1]
	v_pk_mul_f32 v[116:117], v[34:35], v[26:27] op_sel_hi:[0,1]
	v_pk_mul_f32 v[112:113], v[34:35], v[24:25] op_sel_hi:[0,1]
	v_pk_mul_f32 v[108:109], v[34:35], v[22:23] op_sel_hi:[0,1]
	v_pk_mul_f32 v[104:105], v[34:35], v[20:21] op_sel_hi:[0,1]
	v_pk_mul_f32 v[100:101], v[34:35], v[18:19] op_sel_hi:[0,1]
	v_pk_mul_f32 v[96:97], v[34:35], v[16:17] op_sel_hi:[0,1]
	v_pk_mul_f32 v[122:123], v[34:35], v[14:15] op_sel_hi:[0,1]
	v_pk_mul_f32 v[118:119], v[34:35], v[12:13] op_sel_hi:[0,1]
	v_pk_mul_f32 v[114:115], v[34:35], v[10:11] op_sel_hi:[0,1]
	v_pk_mul_f32 v[110:111], v[34:35], v[8:9] op_sel_hi:[0,1]
	v_pk_mul_f32 v[106:107], v[34:35], v[6:7] op_sel_hi:[0,1]
	v_pk_mul_f32 v[102:103], v[34:35], v[4:5] op_sel_hi:[0,1]
	v_pk_mul_f32 v[98:99], v[34:35], v[2:3] op_sel_hi:[0,1]
	v_pk_mul_f32 v[94:95], v[34:35], v[0:1] op_sel_hi:[0,1]
	v_mov_b32_e32 v31, 0
	s_cbranch_vccnz .LBB0_811
; #define LAS __attribute__((address_space(3)))
; DI f32x16 mma32(bf16x8 a, bf16x8 b, f32x16 c) { return __builtin_amdgcn_mfma_f32_32x32x16_bf16(a, b, c, 0, 0, 0); }
; DI int crow(int i, int hf) { return (i & 3) + 8 * (i >> 2) + 4 * hf; }
; DI void nsa_item(KA a, LAS unsigned char* lds, const int it) {
;     ...
;     float m_ref = 0.f, l_run = 0.f; f32x16 ot[2] = {ZERO16, ZERO16}; int curtype = 0;
;     for (int i = 0; i < n; ++i) {
;         const int desc = LIST[i]; const int ty = desc >> 8, j = desc & 255;
;         const LAS bf16* Kc = (i & 1) ? Kt1 : Kt; const LAS bf16* Vc = (i & 1) ? VT1 : VT;
;         if (ty != curtype) { const float lt = l_run + __shfl_xor(l_run, 32); const float sc = g1 / lt; of[0] += ot[0] * sc; of[1] += ot[1] * sc; ot[0] = ZERO16; ot[1] = ZERO16; m_ref = 0.f; l_run = 0.f; curtype = ty; }
;         const bool rowoff = (ty == 0) && (((mysel >> j) & 1u) == 0u);
;         const int mode = (j == qb) ? 1 : ((ty == 1 && j == qb - 8) ? 2 : 0);
;         const float init = rowoff ? -INFINITY : -m_ref;
;         f32x16 st[2];
; #pragma unroll
;         for (int i2 = 0; i2 < 16; ++i2) { st[0][i2] = init; st[1][i2] = init; }
; #pragma unroll
;         for (int kt = 0; kt < 2; ++kt)
; #pragma unroll
;             for (int s = 0; s < 4; ++s) { const bf16x8 af = *(const LAS bf16x8*)(Kc + (32 * kt + r) * PA + 16 * s + 8 * hf); st[kt] = mma32(af, bq[s], st[kt]); }
;         if (mode != 0) {
; #pragma unroll
;             for (int kt = 0; kt < 2; ++kt)
; #pragma unroll
;                 for (int i2 = 0; i2 < 16; ++i2) { const int kl = 32 * kt + crow(i2, hf); const bool bad = rowoff || (mode == 1 && kl > tql) || (mode == 2 && kl <= tql); st[kt][i2] = bad ? -INFINITY : st[kt][i2]; }
	v_cmp_gt_u32_e64 s[0:1], v92, v135
	v_or_b32_e32 v0, 2, v92
	s_sub_i32 s85, 23, s40
	v_writelane_b32 v254, s0, 49
	s_mov_b32 s87, 0
	s_mov_b32 s88, 0
	v_writelane_b32 v254, s1, 50
	v_cmp_le_u32_e64 s[0:1], v92, v135
	v_mov_b32_e32 v137, 0
	v_mov_b32_e32 v16, 0
	v_writelane_b32 v254, s0, 51
	s_nop 1
	v_writelane_b32 v254, s1, 52
	v_cmp_ge_u32_e64 s[0:1], v92, v135
	s_nop 1
	v_writelane_b32 v254, s0, 53
	s_nop 1
	v_writelane_b32 v254, s1, 54
	v_cmp_lt_u32_e64 s[0:1], v92, v135
	s_nop 1
	v_writelane_b32 v254, s0, 55
	s_nop 1
	v_writelane_b32 v254, s1, 56
	v_cmp_gt_u32_e64 s[0:1], v0, v135
	s_nop 1
	v_writelane_b32 v254, s0, 57
	s_nop 1
	v_writelane_b32 v254, s1, 58
	v_cmp_le_u32_e64 s[0:1], v0, v135
	v_or_b32_e32 v0, 3, v92
	s_nop 0
	v_writelane_b32 v254, s0, 59
	s_nop 1
	v_writelane_b32 v254, s1, 60
	v_cmp_gt_u32_e64 s[0:1], v0, v135
	s_nop 1
	v_writelane_b32 v254, s0, 61
	s_nop 1
	v_writelane_b32 v254, s1, 62
	v_cmp_le_u32_e64 s[0:1], v0, v135
	v_or_b32_e32 v0, 8, v92
	s_nop 0
	v_writelane_b32 v254, s0, 63
	s_nop 0
	v_readlane_b32 s86, v254, 13
	v_writelane_b32 v245, s1, 0
	v_cmp_gt_u32_e64 s[0:1], v0, v135
	s_nop 1
	v_writelane_b32 v245, s0, 1
	s_nop 1
	v_writelane_b32 v245, s1, 2
	v_cmp_le_u32_e64 s[0:1], v0, v135
	v_or_b32_e32 v0, 9, v92
	s_nop 0
	v_writelane_b32 v245, s0, 3
	s_nop 1
	v_writelane_b32 v245, s1, 4
	v_cmp_gt_u32_e64 s[0:1], v0, v135
	s_nop 1
	v_writelane_b32 v245, s0, 5
	s_nop 1
	v_writelane_b32 v245, s1, 6
	v_cmp_le_u32_e64 s[0:1], v0, v135
	v_or_b32_e32 v0, 10, v92
	s_nop 0
	v_writelane_b32 v245, s0, 7
	s_nop 1
	v_writelane_b32 v245, s1, 8
	v_cmp_gt_u32_e64 s[0:1], v0, v135
	s_nop 1
	v_writelane_b32 v245, s0, 9
	s_nop 1
	v_writelane_b32 v245, s1, 10
	v_cmp_le_u32_e64 s[0:1], v0, v135
	v_or_b32_e32 v0, 11, v92
	s_nop 0
	v_writelane_b32 v245, s0, 11
	s_nop 1
	v_writelane_b32 v245, s1, 12
	v_cmp_gt_u32_e64 s[0:1], v0, v135
	s_nop 1
	v_writelane_b32 v245, s0, 13
	s_nop 1
	v_writelane_b32 v245, s1, 14
	v_cmp_le_u32_e64 s[0:1], v0, v135
	v_or_b32_e32 v0, 16, v92
	s_nop 0
	v_writelane_b32 v245, s0, 15
	s_nop 1
	v_writelane_b32 v245, s1, 16
	v_cmp_gt_u32_e64 s[0:1], v0, v135
	s_nop 1
	v_writelane_b32 v245, s0, 17
	s_nop 1
	v_writelane_b32 v245, s1, 18
	v_cmp_le_u32_e64 s[0:1], v0, v135
	v_or_b32_e32 v0, 17, v92
	s_nop 0
	v_writelane_b32 v245, s0, 19
	s_nop 1
	v_writelane_b32 v245, s1, 20
	v_cmp_gt_u32_e64 s[0:1], v0, v135
	s_nop 1
	v_writelane_b32 v245, s0, 21
	s_nop 1
	v_writelane_b32 v245, s1, 22
	v_cmp_le_u32_e64 s[0:1], v0, v135
	v_or_b32_e32 v0, 18, v92
	s_nop 0
	v_writelane_b32 v245, s0, 23
	s_nop 1
	v_writelane_b32 v245, s1, 24
	v_cmp_gt_u32_e64 s[0:1], v0, v135
	s_nop 1
	v_writelane_b32 v245, s0, 25
	s_nop 1
	v_writelane_b32 v245, s1, 26
	v_cmp_le_u32_e64 s[0:1], v0, v135
	v_or_b32_e32 v0, 19, v92
	s_nop 0
	v_writelane_b32 v245, s0, 27
	s_nop 1
	v_writelane_b32 v245, s1, 28
	v_cmp_gt_u32_e64 s[0:1], v0, v135
	s_nop 1
	v_writelane_b32 v245, s0, 29
	s_nop 1
	v_writelane_b32 v245, s1, 30
	v_cmp_le_u32_e64 s[0:1], v0, v135
	v_or_b32_e32 v0, 24, v92
	s_nop 0
	v_writelane_b32 v245, s0, 31
	s_nop 1
	v_writelane_b32 v245, s1, 32
	v_cmp_gt_u32_e64 s[0:1], v0, v135
	s_nop 1
	v_writelane_b32 v245, s0, 33
	s_nop 1
	v_writelane_b32 v245, s1, 34
	v_cmp_le_u32_e64 s[0:1], v0, v135
	v_or_b32_e32 v0, 25, v92
	v_cmp_gt_u32_e64 s[92:93], v0, v135
	v_cmp_le_u32_e64 s[94:95], v0, v135
	v_or_b32_e32 v0, 26, v92
	v_cmp_gt_u32_e64 s[96:97], v0, v135
	v_cmp_le_u32_e64 s[6:7], v0, v135
	v_or_b32_e32 v0, 27, v92
	v_cmp_gt_u32_e64 s[8:9], v0, v135
	v_cmp_le_u32_e64 s[10:11], v0, v135
	v_or_b32_e32 v0, 32, v92
	v_cmp_gt_u32_e64 s[12:13], v0, v135
	v_cmp_le_u32_e64 s[14:15], v0, v135
	v_or_b32_e32 v0, 33, v92
	v_cmp_gt_u32_e64 s[16:17], v0, v135
	v_cmp_le_u32_e64 s[18:19], v0, v135
	v_or_b32_e32 v0, 34, v92
	v_cmp_gt_u32_e64 s[20:21], v0, v135
	v_cmp_le_u32_e64 s[22:23], v0, v135
	v_or_b32_e32 v0, 35, v92
	v_cmp_gt_u32_e64 s[24:25], v0, v135
	v_cmp_le_u32_e64 s[26:27], v0, v135
	v_or_b32_e32 v0, 40, v92
	v_cmp_gt_u32_e64 s[28:29], v0, v135
	v_cmp_le_u32_e64 s[30:31], v0, v135
	v_or_b32_e32 v0, 41, v92
	v_cmp_gt_u32_e64 s[34:35], v0, v135
	v_cmp_le_u32_e64 s[36:37], v0, v135
	v_or_b32_e32 v0, 42, v92
	v_cmp_gt_u32_e64 s[38:39], v0, v135
	v_cmp_le_u32_e64 s[4:5], v0, v135
	v_or_b32_e32 v0, 43, v92
	v_writelane_b32 v245, s0, 35
	v_cmp_gt_u32_e64 s[40:41], v0, v135
	v_cmp_le_u32_e64 s[2:3], v0, v135
	v_or_b32_e32 v0, 48, v92
	v_writelane_b32 v245, s1, 36
	v_cmp_gt_u32_e64 s[0:1], v0, v135
	v_cmp_le_u32_e64 s[42:43], v0, v135
	v_or_b32_e32 v0, 49, v92
	v_cmp_gt_u32_e64 s[44:45], v0, v135
	v_cmp_le_u32_e64 s[46:47], v0, v135
	v_or_b32_e32 v0, 50, v92
	v_cmp_gt_u32_e64 s[48:49], v0, v135
	v_cmp_le_u32_e64 s[50:51], v0, v135
	v_or_b32_e32 v0, 51, v92
	v_cmp_gt_u32_e64 s[52:53], v0, v135
	v_cmp_le_u32_e64 s[54:55], v0, v135
	v_or_b32_e32 v0, 56, v92
	v_cmp_gt_u32_e64 s[56:57], v0, v135
	v_cmp_le_u32_e64 s[58:59], v0, v135
	v_or_b32_e32 v0, 57, v92
	v_cmp_gt_u32_e64 s[60:61], v0, v135
	v_cmp_le_u32_e64 s[62:63], v0, v135
	v_or_b32_e32 v0, 58, v92
	v_cmp_gt_u32_e64 s[64:65], v0, v135
	v_cmp_le_u32_e64 s[66:67], v0, v135
	v_or_b32_e32 v0, 59, v92
	v_cmp_gt_u32_e64 s[68:69], v0, v135
	v_cmp_le_u32_e64 s[70:71], v0, v135
	v_mov_b32_e32 v135, 0
	v_mov_b32_e32 v0, 0
	v_mov_b32_e32 v1, v135
	v_mov_b32_e32 v2, v135
	v_mov_b32_e32 v3, v135
	v_mov_b32_e32 v4, v135
	v_mov_b32_e32 v5, v135
	v_mov_b32_e32 v6, v135
	v_mov_b32_e32 v7, v135
	v_mov_b32_e32 v8, v135
	v_mov_b32_e32 v9, v135
	v_mov_b32_e32 v10, v135
	v_mov_b32_e32 v11, v135
	v_mov_b32_e32 v12, v135
	v_mov_b32_e32 v13, v135
	v_mov_b32_e32 v14, v135
	v_mov_b32_e32 v15, v135
	v_mov_b32_e32 v17, v135
	v_mov_b32_e32 v18, v135
	v_mov_b32_e32 v19, v135
	v_mov_b32_e32 v20, v135
	v_mov_b32_e32 v21, v135
	v_mov_b32_e32 v22, v135
	v_mov_b32_e32 v23, v135
	v_mov_b32_e32 v24, v135
	v_mov_b32_e32 v25, v135
	v_mov_b32_e32 v26, v135
	v_mov_b32_e32 v27, v135
	v_mov_b32_e32 v28, v135
	v_mov_b32_e32 v29, v135
	v_mov_b32_e32 v30, v135
	v_mov_b32_e32 v31, v135
	s_add_i32 s74, s86, -8
	v_mov_b32_e32 v191, s74
	ds_read_b32 v191, v191
	v_mov_b32_e32 v250, s86
	ds_read_b32 v250, v250
	v_add3_u32 v231, 0, v90, v130
	s_movk_i32 s74, 0x4800
	v_add3_u32 v230, s74, v90, v131
	s_waitcnt lgkmcnt(0)

; #define NSA_STORE(Kb, Vb) do { *(LAS v4u*)((Kb) + skey * PA + 8 * sch) = kreg; LAS unsigned* d0_ = (LAS unsigned*)((Vb) + (4 * sdg) * PV + vpos(2 * skp)); \
;         d0_[0] = (vr0.x & 0xffffu) | (vr1.x << 16); d0_[PV / 2] = (vr0.x >> 16) | (vr1.x & 0xffff0000u); d0_[PV] = (vr0.y & 0xffffu) | (vr1.y << 16); d0_[3 * PV / 2] = (vr0.y >> 16) | (vr1.y & 0xffff0000u); } while (0)
; DI void nsa_item(KA a, LAS unsigned char* lds, const int it) {
;     ...
;         if (i + 1 < n) { if (i & 1) NSA_STORE(Kt, VT); else NSA_STORE(Kt1, VT1); if (i + 2 < n) NSA_LOAD(LIST[i + 2]); }
;         __syncthreads();
.LBB0_806:
	v_mov_b32_e32 v80, v250
	s_movk_i32 s75, 0xbb0
	s_movk_i32 s79, 0x1c00
	v_lshlrev_b32_e32 v81, 6, v80
	v_readfirstlane_b32 s74, v80
	v_and_b32_e32 v80, 0x3fc0, v81
	s_cmpk_lt_u32 s74, 0x100
	v_readlane_b32 s74, v254, 48
	s_cselect_b32 s75, s75, 0xcb0
	s_nop 0
	v_add_u32_e32 v89, s74, v80
	s_movk_i32 s74, 0xb30
	s_cselect_b32 s74, s74, 0xc30
	s_or_b32 s77, s74, s33
	s_or_b32 s78, s75, s33
	v_readlane_b32 s74, v254, 39
	v_readlane_b32 s75, v254, 40
	v_add_u32_e32 v82, v89, v132
	s_lshl_b32 s90, s77, 1
	v_mov_b64_e32 v[80:81], s[74:75]
	v_mad_i64_i32 v[82:83], s[74:75], v82, s79, v[80:81]
	v_add_u32_e32 v89, v89, v133
	v_lshl_add_u64 v[82:83], v[82:83], 0, s[90:91]
	v_mad_i64_i32 v[80:81], s[74:75], v89, s79, v[80:81]
	s_lshl_b32 s90, s78, 1
	v_lshl_add_u64 v[80:81], v[80:81], 0, s[90:91]
	v_mov_b32_e32 v89, v193
	v_lshl_add_u64 v[82:83], v[82:83], 0, v[192:193]
	v_lshl_add_u64 v[128:129], v[80:81], 0, v[88:89]
	global_load_dwordx4 v[80:83], v[82:83], off
	s_nop 0
	global_load_dwordx2 v[126:127], v[128:129], off
	v_add_co_u32_e32 v128, vcc, 0x1000, v128
	v_readlane_b32 s90, v254, 47
	s_nop 0
	v_addc_co_u32_e32 v129, vcc, 0, v129, vcc
	global_load_dwordx2 v[128:129], v[128:129], off offset:3072
.LBB0_807:
	s_add_i32 s86, s86, 4
	s_add_i32 s74, s86, -8
	v_mov_b32_e32 v191, s74
	ds_read_b32 v191, v191
	v_mov_b32_e32 v250, s86
	ds_read_b32 v250, v250
	s_bitcmp1_b32 s76, 0
	s_cselect_b32 s74, 0x9000, 0
	s_movk_i32 s75, 0x4800
	s_cselect_b32 s75, 0xb400, s75
	v_add3_u32 v231, s74, v90, v130
	v_add3_u32 v230, s75, v90, v131
	v_pk_add_f32 v[48:49], v[48:49], v[50:51]
	v_pk_add_f32 v[52:53], v[52:53], v[54:55]
	v_pk_add_f32 v[56:57], v[56:57], v[58:59]
	v_pk_add_f32 v[60:61], v[60:61], v[62:63]
	v_pk_add_f32 v[32:33], v[32:33], v[34:35]
	v_pk_add_f32 v[36:37], v[36:37], v[38:39]
	v_pk_add_f32 v[40:41], v[40:41], v[42:43]
	v_pk_add_f32 v[44:45], v[44:45], v[46:47]
	v_pk_add_f32 v[48:49], v[48:49], v[52:53]
	v_pk_add_f32 v[56:57], v[56:57], v[60:61]
	v_pk_add_f32 v[32:33], v[32:33], v[36:37]
	v_pk_add_f32 v[40:41], v[40:41], v[44:45]
	s_cmp_lg_u32 s84, s76
	s_waitcnt lgkmcnt(0)
	s_barrier
	v_pk_add_f32 v[48:49], v[48:49], v[56:57]
	v_pk_add_f32 v[32:33], v[32:33], v[40:41]
	s_nop 0
	v_pk_add_f32 v[32:33], v[32:33], v[48:49]
	s_nop 0
	v_add_f32_e32 v32, v32, v33
	v_add_f32_e32 v135, v135, v32
	s_cbranch_scc0 .LBB0_600
	s_mov_b32 s87, s76
	s_branch .LBB0_796
